# v44 + nt on the 32 once-read f32 residual base loads in the residual-GEMM epilogue
# baseline (speedup 1.0000x reference)
;     __device__ __forceinline__ void operator()(const f32x4 (&acc)[2][2][4][2], const Unit& u, int wr, int wc, int fr, int fq) const {
;     ...
;         f32x4 xb[3][2][2];
; #pragma unroll
;         for (int pr = 0; pr < 2; ++pr)
; #pragma unroll
;             for (int bj = 0; bj < 2; ++bj)
; #pragma unroll
;                 for (int n = 0; n < 2; ++n) xb[pr][bj][n] = *(const f32x4*)(base + (size_t)(row0 + pr * 16) * ldc + col0 + bj * HALF + n * 16);
; #pragma unroll
;         for (int ai = 0; ai < 2; ++ai)
; #pragma unroll
;             for (int m = 0; m < 4; ++m) { const int ri = ai * 4 + m, row = row0 + ai * HALF + m * 16; const size_t off = (size_t)row * ldc + col0;
;                 if (ri < 6) { const int nrow = row0 + ((ri + 2) >> 2) * HALF + ((ri + 2) & 3) * 16;
; #pragma unroll
;                     for (int bj = 0; bj < 2; ++bj)
; #pragma unroll
;                         for (int n = 0; n < 2; ++n) xb[(ri + 2) % 3][bj][n] = *(const f32x4*)(base + (size_t)nrow * ldc + col0 + bj * HALF + n * 16); }
;                 float mu = 0.f, rs = 1.f; if (ln) { mu = tab[(ai * 64 + m * 16 + fr) * 2]; rs = tab[(ai * 64 + m * 16 + fr) * 2 + 1]; }
.LBB0_260:
	v_or_b32_e32 v196, s4, v227
	v_or_b32_e32 v194, s5, v183
	v_ashrrev_i32_e32 v197, 31, v196
	v_lshlrev_b64 v[90:91], 2, v[196:197]
	v_ashrrev_i32_e32 v195, 31, v194
	v_lshl_add_u64 v[92:93], s[56:57], 0, v[90:91]
	v_lshlrev_b64 v[134:135], 13, v[194:195]
	v_or_b32_e32 v200, 16, v194
	v_lshl_add_u64 v[134:135], v[92:93], 0, v[134:135]
	v_ashrrev_i32_e32 v201, 31, v200
	global_load_dwordx4 v[178:181], v[134:135], off nt
	global_load_dwordx4 v[158:161], v[134:135], off offset:64 nt
	global_load_dwordx4 v[150:153], v[134:135], off offset:512 nt
	global_load_dwordx4 v[142:145], v[134:135], off offset:576 nt
	v_lshlrev_b64 v[134:135], 13, v[200:201]
	v_or_b32_e32 v198, 32, v194
	v_lshl_add_u64 v[92:93], v[92:93], 0, v[134:135]
	v_ashrrev_i32_e32 v199, 31, v198
	global_load_dwordx4 v[174:177], v[92:93], off nt
	global_load_dwordx4 v[170:173], v[92:93], off offset:64 nt
	global_load_dwordx4 v[166:169], v[92:93], off offset:512 nt
	global_load_dwordx4 v[162:165], v[92:93], off offset:576 nt
	v_lshlrev_b64 v[92:93], 13, v[198:199]
	v_lshl_add_u64 v[92:93], s[56:57], 0, v[92:93]
	v_lshl_add_u64 v[90:91], v[92:93], 0, v[90:91]
	global_load_dwordx4 v[154:157], v[90:91], off nt
	global_load_dwordx4 v[146:149], v[90:91], off offset:64 nt
	global_load_dwordx4 v[138:141], v[90:91], off offset:512 nt
	global_load_dwordx4 v[134:137], v[90:91], off offset:576 nt
	s_and_b64 vcc, exec, s[40:41]
	s_cbranch_vccnz .LBB0_262
	ds_read_b64 v[202:203], v234
	s_waitcnt lgkmcnt(0)
	v_mov_b32_e32 v204, v203
	s_and_b64 vcc, exec, s[40:41]
	v_mov_b32_e32 v205, v204
	s_cbranch_vccz .LBB0_263
	s_branch .LBB0_264

;     __device__ __forceinline__ void operator()(const f32x4 (&acc)[2][2][4][2], const Unit& u, int wr, int wc, int fr, int fq) const {
;     ...
;         for (int ai = 0; ai < 2; ++ai)
; #pragma unroll
;             for (int m = 0; m < 4; ++m) { const int ri = ai * 4 + m, row = row0 + ai * HALF + m * 16; const size_t off = (size_t)row * ldc + col0;
;                 if (ri < 6) { const int nrow = row0 + ((ri + 2) >> 2) * HALF + ((ri + 2) & 3) * 16;
; #pragma unroll
;                     for (int bj = 0; bj < 2; ++bj)
; #pragma unroll
;                         for (int n = 0; n < 2; ++n) xb[(ri + 2) % 3][bj][n] = *(const f32x4*)(base + (size_t)nrow * ldc + col0 + bj * HALF + n * 16); }
;                 float mu = 0.f, rs = 1.f; if (ln) { mu = tab[(ai * 64 + m * 16 + fr) * 2]; rs = tab[(ai * 64 + m * 16 + fr) * 2 + 1]; }
.LBB0_272:
	s_or_b64 exec, exec, s[0:1]
	v_or_b32_e32 v178, 48, v194
	v_ashrrev_i32_e32 v179, 31, v178
	v_lshlrev_b64 v[130:131], 13, v[178:179]
	v_lshl_add_u64 v[130:131], s[56:57], 0, v[130:131]
	v_lshl_add_u64 v[130:131], v[196:197], 2, v[130:131]
	global_load_dwordx4 v[158:161], v[130:131], off nt
	global_load_dwordx4 v[150:153], v[130:131], off offset:64 nt
	global_load_dwordx4 v[142:145], v[130:131], off offset:512 nt
	s_waitcnt lgkmcnt(0)
	global_load_dwordx4 v[130:133], v[130:131], off offset:576 nt
	s_and_b64 vcc, exec, s[40:41]
	s_cbranch_vccnz .LBB0_274
	ds_read_b64 v[180:181], v234 offset:128
	s_waitcnt lgkmcnt(0)
	v_mov_b32_e32 v202, v181
	s_and_b64 vcc, exec, s[40:41]
	v_mov_b32_e32 v203, v202
	s_cbranch_vccz .LBB0_275
	s_branch .LBB0_276

;     __device__ __forceinline__ void operator()(const f32x4 (&acc)[2][2][4][2], const Unit& u, int wr, int wc, int fr, int fq) const {
;     ...
;         for (int ai = 0; ai < 2; ++ai)
; #pragma unroll
;             for (int m = 0; m < 4; ++m) { const int ri = ai * 4 + m, row = row0 + ai * HALF + m * 16; const size_t off = (size_t)row * ldc + col0;
;                 if (ri < 6) { const int nrow = row0 + ((ri + 2) >> 2) * HALF + ((ri + 2) & 3) * 16;
; #pragma unroll
;                     for (int bj = 0; bj < 2; ++bj)
; #pragma unroll
;                         for (int n = 0; n < 2; ++n) xb[(ri + 2) % 3][bj][n] = *(const f32x4*)(base + (size_t)nrow * ldc + col0 + bj * HALF + n * 16); }
;                 float mu = 0.f, rs = 1.f; if (ln) { mu = tab[(ai * 64 + m * 16 + fr) * 2]; rs = tab[(ai * 64 + m * 16 + fr) * 2 + 1]; }
.LBB0_284:
	s_or_b64 exec, exec, s[0:1]
	v_add_u32_e32 v162, 0x80, v194
	v_ashrrev_i32_e32 v163, 31, v162
	v_lshlrev_b64 v[114:115], 13, v[162:163]
	v_lshl_add_u64 v[114:115], s[56:57], 0, v[114:115]
	v_lshl_add_u64 v[114:115], v[196:197], 2, v[114:115]
	global_load_dwordx4 v[126:129], v[114:115], off nt
	global_load_dwordx4 v[122:125], v[114:115], off offset:64 nt
	global_load_dwordx4 v[118:121], v[114:115], off offset:512 nt
	s_waitcnt lgkmcnt(0)
	global_load_dwordx4 v[114:117], v[114:115], off offset:576 nt
	s_and_b64 vcc, exec, s[40:41]
	s_cbranch_vccnz .LBB0_286
	ds_read_b64 v[164:165], v234 offset:256
	s_waitcnt lgkmcnt(0)
	v_mov_b32_e32 v166, v165
	s_and_b64 vcc, exec, s[40:41]
	v_mov_b32_e32 v167, v166
	s_cbranch_vccz .LBB0_287
	s_branch .LBB0_288

;     __device__ __forceinline__ void operator()(const f32x4 (&acc)[2][2][4][2], const Unit& u, int wr, int wc, int fr, int fq) const {
;     ...
;         for (int ai = 0; ai < 2; ++ai)
; #pragma unroll
;             for (int m = 0; m < 4; ++m) { const int ri = ai * 4 + m, row = row0 + ai * HALF + m * 16; const size_t off = (size_t)row * ldc + col0;
;                 if (ri < 6) { const int nrow = row0 + ((ri + 2) >> 2) * HALF + ((ri + 2) & 3) * 16;
; #pragma unroll
;                     for (int bj = 0; bj < 2; ++bj)
; #pragma unroll
;                         for (int n = 0; n < 2; ++n) xb[(ri + 2) % 3][bj][n] = *(const f32x4*)(base + (size_t)nrow * ldc + col0 + bj * HALF + n * 16); }
;                 float mu = 0.f, rs = 1.f; if (ln) { mu = tab[(ai * 64 + m * 16 + fr) * 2]; rs = tab[(ai * 64 + m * 16 + fr) * 2 + 1]; }
.LBB0_296:
	s_or_b64 exec, exec, s[0:1]
	v_add_u32_e32 v134, 0x90, v194
	v_ashrrev_i32_e32 v135, 31, v134
	v_lshlrev_b64 v[80:81], 13, v[134:135]
	v_lshl_add_u64 v[80:81], s[56:57], 0, v[80:81]
	v_lshl_add_u64 v[80:81], v[196:197], 2, v[80:81]
	global_load_dwordx4 v[110:113], v[80:81], off nt
	global_load_dwordx4 v[98:101], v[80:81], off offset:64 nt
	global_load_dwordx4 v[86:89], v[80:81], off offset:512 nt
	s_waitcnt lgkmcnt(0)
	global_load_dwordx4 v[80:83], v[80:81], off offset:576 nt
	s_and_b64 vcc, exec, s[40:41]
	s_cbranch_vccnz .LBB0_298
	ds_read_b64 v[140:141], v234 offset:384
	s_waitcnt lgkmcnt(0)
	v_mov_b32_e32 v146, v141
	s_and_b64 vcc, exec, s[40:41]
	v_mov_b32_e32 v147, v146
	s_cbranch_vccz .LBB0_299
	s_branch .LBB0_300

;     __device__ __forceinline__ void operator()(const f32x4 (&acc)[2][2][4][2], const Unit& u, int wr, int wc, int fr, int fq) const {
;     ...
;         for (int ai = 0; ai < 2; ++ai)
; #pragma unroll
;             for (int m = 0; m < 4; ++m) { const int ri = ai * 4 + m, row = row0 + ai * HALF + m * 16; const size_t off = (size_t)row * ldc + col0;
;                 if (ri < 6) { const int nrow = row0 + ((ri + 2) >> 2) * HALF + ((ri + 2) & 3) * 16;
; #pragma unroll
;                     for (int bj = 0; bj < 2; ++bj)
; #pragma unroll
;                         for (int n = 0; n < 2; ++n) xb[(ri + 2) % 3][bj][n] = *(const f32x4*)(base + (size_t)nrow * ldc + col0 + bj * HALF + n * 16); }
;                 float mu = 0.f, rs = 1.f; if (ln) { mu = tab[(ai * 64 + m * 16 + fr) * 2]; rs = tab[(ai * 64 + m * 16 + fr) * 2 + 1]; }
.LBB0_308:
	s_or_b64 exec, exec, s[0:1]
	v_or_b32_e32 v64, 32, v162
	v_ashrrev_i32_e32 v65, 31, v64
	v_lshlrev_b64 v[64:65], 13, v[64:65]
	v_lshl_add_u64 v[64:65], s[56:57], 0, v[64:65]
	v_lshl_add_u64 v[64:65], v[196:197], 2, v[64:65]
	global_load_dwordx4 v[76:79], v[64:65], off nt
	global_load_dwordx4 v[72:75], v[64:65], off offset:64 nt
	global_load_dwordx4 v[68:71], v[64:65], off offset:512 nt
	s_waitcnt lgkmcnt(0)
	global_load_dwordx4 v[64:67], v[64:65], off offset:576 nt
	s_and_b64 vcc, exec, s[40:41]
	s_cbranch_vccnz .LBB0_310
	ds_read_b64 v[130:131], v234 offset:512
	s_waitcnt lgkmcnt(0)
	v_mov_b32_e32 v132, v131
	s_and_b64 vcc, exec, s[40:41]
	v_mov_b32_e32 v133, v132
	s_cbranch_vccz .LBB0_311
	s_branch .LBB0_312

;     __device__ __forceinline__ void operator()(const f32x4 (&acc)[2][2][4][2], const Unit& u, int wr, int wc, int fr, int fq) const {
;     ...
;         for (int ai = 0; ai < 2; ++ai)
; #pragma unroll
;             for (int m = 0; m < 4; ++m) { const int ri = ai * 4 + m, row = row0 + ai * HALF + m * 16; const size_t off = (size_t)row * ldc + col0;
;                 if (ri < 6) { const int nrow = row0 + ((ri + 2) >> 2) * HALF + ((ri + 2) & 3) * 16;
; #pragma unroll
;                     for (int bj = 0; bj < 2; ++bj)
; #pragma unroll
;                         for (int n = 0; n < 2; ++n) xb[(ri + 2) % 3][bj][n] = *(const f32x4*)(base + (size_t)nrow * ldc + col0 + bj * HALF + n * 16); }
;                 float mu = 0.f, rs = 1.f; if (ln) { mu = tab[(ai * 64 + m * 16 + fr) * 2]; rs = tab[(ai * 64 + m * 16 + fr) * 2 + 1]; }
.LBB0_320:
	s_or_b64 exec, exec, s[0:1]
	v_or_b32_e32 v48, 48, v162
	v_ashrrev_i32_e32 v49, 31, v48
	v_lshlrev_b64 v[48:49], 13, v[48:49]
	v_lshl_add_u64 v[48:49], s[56:57], 0, v[48:49]
	v_lshl_add_u64 v[48:49], v[196:197], 2, v[48:49]
	global_load_dwordx4 v[60:63], v[48:49], off nt
	global_load_dwordx4 v[56:59], v[48:49], off offset:64 nt
	global_load_dwordx4 v[52:55], v[48:49], off offset:512 nt
	s_waitcnt lgkmcnt(0)
	global_load_dwordx4 v[48:51], v[48:49], off offset:576 nt
	s_and_b64 vcc, exec, s[40:41]
	s_cbranch_vccnz .LBB0_322
	ds_read_b64 v[114:115], v234 offset:640
	s_waitcnt lgkmcnt(0)
	v_mov_b32_e32 v116, v115
	s_and_b64 vcc, exec, s[40:41]
	v_mov_b32_e32 v117, v116
	s_cbranch_vccz .LBB0_323
	s_branch .LBB0_324
